# v8 + K-loop MMA segments slimmed: redundant post-barrier s_waitcnt lgkmcnt(0) and the mid-segment s_setprio 0/1 pair removed
# speedup vs baseline: 1.0056x; 1.0056x over previous
.LBB0_344:
	s_add_i32 s4, s2, 2
	s_add_u32 s5, s68, s0
	s_addc_u32 s3, s69, s1
	s_add_u32 s33, s86, s0
	s_addc_u32 s35, s87, s1
	s_add_i32 s47, 0, 0x10000
	s_cmp_eq_u32 s21, s2
	s_cselect_b32 s3, s65, s3
	s_cselect_b32 s2, s64, s5
	v_add_u32_e32 v17, s47, v237
	s_cselect_b32 s57, s67, s35
	s_cselect_b32 s56, s66, s33
	s_add_i32 s5, 0, 0x14000
	ds_read_b128 v[134:137], v17
	ds_read_b128 v[138:141], v17 offset:1024
	ds_read_b128 v[142:145], v17 offset:2048
	ds_read_b128 v[146:149], v17 offset:3072
	v_add_u32_e32 v17, s5, v237
	ds_read_b128 v[150:153], v17
	ds_read_b128 v[154:157], v17 offset:1024
	ds_read_b128 v[158:161], v17 offset:2048
	ds_read_b128 v[162:165], v17 offset:3072
	v_lshl_add_u64 v[170:171], s[68:69], 0, v[132:133]
	s_add_i32 m0, s37, 0xc000
	ds_read_b128 v[166:169], v240
	ds_read_b128 v[186:189], v240 offset:1024
	ds_read_b128 v[190:193], v240 offset:2048
	ds_read_b128 v[194:197], v240 offset:3072
	ds_read_b128 v[198:201], v240 offset:4096
	ds_read_b128 v[202:205], v240 offset:5120
	ds_read_b128 v[206:209], v240 offset:6144
	ds_read_b128 v[210:213], v240 offset:7168
	global_load_lds_dwordx4 v[170:171], off
	v_lshl_add_u64 v[170:171], s[68:69], 0, v[18:19]
	s_add_i32 m0, s37, 0xe000
	s_nop 0
	global_load_lds_dwordx4 v[170:171], off
	s_waitcnt vmcnt(8)
	s_waitcnt lgkmcnt(0)
	s_barrier
	s_setprio 1
	v_mfma_f32_16x16x32_bf16 v[8:11], v[134:137], v[166:169], v[8:11]
	v_mfma_f32_16x16x32_bf16 v[12:15], v[142:145], v[166:169], v[12:15]
	v_mfma_f32_16x16x32_bf16 v[28:31], v[134:137], v[190:193], v[28:31]
	v_mfma_f32_16x16x32_bf16 v[32:35], v[142:145], v[190:193], v[32:35]
	v_mfma_f32_16x16x32_bf16 v[36:39], v[134:137], v[198:201], v[36:39]
	v_mfma_f32_16x16x32_bf16 v[44:47], v[142:145], v[198:201], v[44:47]
	v_mfma_f32_16x16x32_bf16 v[80:83], v[134:137], v[206:209], v[80:83]
	v_mfma_f32_16x16x32_bf16 v[88:91], v[142:145], v[206:209], v[88:91]
	v_mfma_f32_16x16x32_bf16 v[8:11], v[138:141], v[186:189], v[8:11]
	v_mfma_f32_16x16x32_bf16 v[12:15], v[146:149], v[186:189], v[12:15]
	v_mfma_f32_16x16x32_bf16 v[28:31], v[138:141], v[194:197], v[28:31]
	v_mfma_f32_16x16x32_bf16 v[32:35], v[146:149], v[194:197], v[32:35]
	v_mfma_f32_16x16x32_bf16 v[36:39], v[138:141], v[202:205], v[36:39]
	v_mfma_f32_16x16x32_bf16 v[44:47], v[146:149], v[202:205], v[44:47]
	v_mfma_f32_16x16x32_bf16 v[80:83], v[138:141], v[210:213], v[80:83]
	v_mfma_f32_16x16x32_bf16 v[88:91], v[146:149], v[210:213], v[88:91]
	v_mfma_f32_16x16x32_bf16 v[0:3], v[150:153], v[166:169], v[0:3]
	v_mfma_f32_16x16x32_bf16 v[4:7], v[158:161], v[166:169], v[4:7]
	v_mfma_f32_16x16x32_bf16 v[20:23], v[150:153], v[190:193], v[20:23]
	v_mfma_f32_16x16x32_bf16 v[24:27], v[158:161], v[190:193], v[24:27]
	v_mfma_f32_16x16x32_bf16 v[40:43], v[150:153], v[198:201], v[40:43]
	v_mfma_f32_16x16x32_bf16 v[48:51], v[158:161], v[198:201], v[48:51]
	v_mfma_f32_16x16x32_bf16 v[60:63], v[150:153], v[206:209], v[60:63]
	v_mfma_f32_16x16x32_bf16 v[64:67], v[158:161], v[206:209], v[64:67]
	v_mfma_f32_16x16x32_bf16 v[0:3], v[154:157], v[186:189], v[0:3]
	v_mfma_f32_16x16x32_bf16 v[4:7], v[162:165], v[186:189], v[4:7]
	v_mfma_f32_16x16x32_bf16 v[20:23], v[154:157], v[194:197], v[20:23]
	v_mfma_f32_16x16x32_bf16 v[24:27], v[162:165], v[194:197], v[24:27]
	v_mfma_f32_16x16x32_bf16 v[40:43], v[154:157], v[202:205], v[40:43]
	v_mfma_f32_16x16x32_bf16 v[48:51], v[162:165], v[202:205], v[48:51]
	v_mfma_f32_16x16x32_bf16 v[60:63], v[154:157], v[210:213], v[60:63]
	v_mfma_f32_16x16x32_bf16 v[64:67], v[162:165], v[210:213], v[64:67]
	s_setprio 0
	s_barrier
	s_add_i32 s33, s47, s17
	v_lshl_add_u64 v[170:171], s[56:57], 0, v[174:175]
	s_mov_b32 m0, s33
	ds_read_b128 v[166:169], v240 offset:16384
	ds_read_b128 v[186:189], v240 offset:17408
	ds_read_b128 v[190:193], v240 offset:18432
	ds_read_b128 v[194:197], v240 offset:19456
	ds_read_b128 v[198:201], v240 offset:20480
	ds_read_b128 v[202:205], v240 offset:21504
	ds_read_b128 v[206:209], v240 offset:22528
	ds_read_b128 v[210:213], v240 offset:23552
	global_load_lds_dwordx4 v[170:171], off
	s_add_i32 m0, s33, 0x2000
	v_lshl_add_u64 v[214:215], s[56:57], 0, v[178:179]
	s_add_u32 s56, s56, s36
	s_addc_u32 s57, s57, 0
	s_add_i32 s5, s5, s17
	global_load_lds_dwordx4 v[214:215], off
	v_lshl_add_u64 v[216:217], s[56:57], 0, v[174:175]
	s_mov_b32 m0, s5
	v_lshl_add_u64 v[224:225], s[56:57], 0, v[178:179]
	global_load_lds_dwordx4 v[216:217], off
	s_add_i32 m0, s5, 0x2000
	v_lshl_add_u64 v[226:227], s[2:3], 0, v[172:173]
	global_load_lds_dwordx4 v[224:225], off
	s_mov_b32 m0, s37
	v_lshl_add_u64 v[242:243], s[2:3], 0, v[176:177]
	global_load_lds_dwordx4 v[226:227], off
	s_mov_b32 m0, s45
	s_nop 0
	global_load_lds_dwordx4 v[242:243], off
	s_waitcnt vmcnt(8)
	s_waitcnt lgkmcnt(0)
	s_barrier
	s_setprio 1
	v_mfma_f32_16x16x32_bf16 v[68:71], v[134:137], v[166:169], v[68:71]
	v_mfma_f32_16x16x32_bf16 v[72:75], v[142:145], v[166:169], v[72:75]
	v_mfma_f32_16x16x32_bf16 v[92:95], v[134:137], v[190:193], v[92:95]
	v_mfma_f32_16x16x32_bf16 v[96:99], v[142:145], v[190:193], v[96:99]
	v_mfma_f32_16x16x32_bf16 v[108:111], v[134:137], v[198:201], v[108:111]
	v_mfma_f32_16x16x32_bf16 v[112:115], v[142:145], v[198:201], v[112:115]
	v_mfma_f32_16x16x32_bf16 v[124:127], v[134:137], v[206:209], v[124:127]
	v_mfma_f32_16x16x32_bf16 v[128:131], v[142:145], v[206:209], v[128:131]
	v_mfma_f32_16x16x32_bf16 v[68:71], v[138:141], v[186:189], v[68:71]
	v_mfma_f32_16x16x32_bf16 v[72:75], v[146:149], v[186:189], v[72:75]
	v_mfma_f32_16x16x32_bf16 v[92:95], v[138:141], v[194:197], v[92:95]
	v_mfma_f32_16x16x32_bf16 v[96:99], v[146:149], v[194:197], v[96:99]
	v_mfma_f32_16x16x32_bf16 v[108:111], v[138:141], v[202:205], v[108:111]
	v_mfma_f32_16x16x32_bf16 v[112:115], v[146:149], v[202:205], v[112:115]
	v_mfma_f32_16x16x32_bf16 v[124:127], v[138:141], v[210:213], v[124:127]
	v_mfma_f32_16x16x32_bf16 v[128:131], v[146:149], v[210:213], v[128:131]
	v_mfma_f32_16x16x32_bf16 v[52:55], v[150:153], v[166:169], v[52:55]
	v_mfma_f32_16x16x32_bf16 v[56:59], v[158:161], v[166:169], v[56:59]
	v_mfma_f32_16x16x32_bf16 v[76:79], v[150:153], v[190:193], v[76:79]
	v_mfma_f32_16x16x32_bf16 v[84:87], v[158:161], v[190:193], v[84:87]
	v_mfma_f32_16x16x32_bf16 v[100:103], v[150:153], v[198:201], v[100:103]
	v_mfma_f32_16x16x32_bf16 v[104:107], v[158:161], v[198:201], v[104:107]
	v_mfma_f32_16x16x32_bf16 v[116:119], v[150:153], v[206:209], v[116:119]
	v_mfma_f32_16x16x32_bf16 v[120:123], v[158:161], v[206:209], v[120:123]
	v_mfma_f32_16x16x32_bf16 v[52:55], v[154:157], v[186:189], v[52:55]
	v_mfma_f32_16x16x32_bf16 v[56:59], v[162:165], v[186:189], v[56:59]
	v_mfma_f32_16x16x32_bf16 v[76:79], v[154:157], v[194:197], v[76:79]
	v_mfma_f32_16x16x32_bf16 v[84:87], v[162:165], v[194:197], v[84:87]
	v_mfma_f32_16x16x32_bf16 v[100:103], v[154:157], v[202:205], v[100:103]
	v_mfma_f32_16x16x32_bf16 v[104:107], v[162:165], v[202:205], v[104:107]
	v_mfma_f32_16x16x32_bf16 v[116:119], v[154:157], v[210:213], v[116:119]
	v_mfma_f32_16x16x32_bf16 v[120:123], v[162:165], v[210:213], v[120:123]
	s_setprio 0
	s_barrier
	s_add_i32 s5, 0, 0x18000
	v_add_u32_e32 v17, s5, v237
	s_add_i32 s33, 0, 0x1c000
	ds_read_b128 v[134:137], v17
	ds_read_b128 v[138:141], v17 offset:1024
	ds_read_b128 v[142:145], v17 offset:2048
	ds_read_b128 v[146:149], v17 offset:3072
	v_add_u32_e32 v17, s33, v237
	ds_read_b128 v[150:153], v17
	ds_read_b128 v[154:157], v17 offset:1024
	ds_read_b128 v[158:161], v17 offset:2048
	ds_read_b128 v[162:165], v17 offset:3072
	s_add_u32 s2, s2, s36
	s_addc_u32 s3, s3, 0
	s_mov_b32 m0, s26
	v_lshl_add_u64 v[244:245], s[2:3], 0, v[172:173]
	ds_read_b128 v[166:169], v240 offset:32768
	ds_read_b128 v[186:189], v240 offset:33792
	ds_read_b128 v[190:193], v240 offset:34816
	ds_read_b128 v[194:197], v240 offset:35840
	ds_read_b128 v[198:201], v240 offset:36864
	ds_read_b128 v[202:205], v240 offset:37888
	ds_read_b128 v[206:209], v240 offset:38912
	ds_read_b128 v[210:213], v240 offset:39936
	global_load_lds_dwordx4 v[244:245], off
	v_lshl_add_u64 v[244:245], s[2:3], 0, v[176:177]
	s_mov_b32 m0, s27
	s_nop 0
	global_load_lds_dwordx4 v[244:245], off
	s_waitcnt vmcnt(8)
	s_waitcnt lgkmcnt(0)
	s_barrier
	s_setprio 1
	v_mfma_f32_16x16x32_bf16 v[8:11], v[134:137], v[166:169], v[8:11]
	v_mfma_f32_16x16x32_bf16 v[12:15], v[142:145], v[166:169], v[12:15]
	v_mfma_f32_16x16x32_bf16 v[28:31], v[134:137], v[190:193], v[28:31]
	v_mfma_f32_16x16x32_bf16 v[32:35], v[142:145], v[190:193], v[32:35]
	v_mfma_f32_16x16x32_bf16 v[36:39], v[134:137], v[198:201], v[36:39]
	v_mfma_f32_16x16x32_bf16 v[44:47], v[142:145], v[198:201], v[44:47]
	v_mfma_f32_16x16x32_bf16 v[80:83], v[134:137], v[206:209], v[80:83]
	v_mfma_f32_16x16x32_bf16 v[88:91], v[142:145], v[206:209], v[88:91]
	v_mfma_f32_16x16x32_bf16 v[8:11], v[138:141], v[186:189], v[8:11]
	v_mfma_f32_16x16x32_bf16 v[12:15], v[146:149], v[186:189], v[12:15]
	v_mfma_f32_16x16x32_bf16 v[28:31], v[138:141], v[194:197], v[28:31]
	v_mfma_f32_16x16x32_bf16 v[32:35], v[146:149], v[194:197], v[32:35]
	v_mfma_f32_16x16x32_bf16 v[36:39], v[138:141], v[202:205], v[36:39]
	v_mfma_f32_16x16x32_bf16 v[44:47], v[146:149], v[202:205], v[44:47]
	v_mfma_f32_16x16x32_bf16 v[80:83], v[138:141], v[210:213], v[80:83]
	v_mfma_f32_16x16x32_bf16 v[88:91], v[146:149], v[210:213], v[88:91]
	v_mfma_f32_16x16x32_bf16 v[0:3], v[150:153], v[166:169], v[0:3]
	v_mfma_f32_16x16x32_bf16 v[4:7], v[158:161], v[166:169], v[4:7]
	v_mfma_f32_16x16x32_bf16 v[20:23], v[150:153], v[190:193], v[20:23]
	v_mfma_f32_16x16x32_bf16 v[24:27], v[158:161], v[190:193], v[24:27]
	v_mfma_f32_16x16x32_bf16 v[40:43], v[150:153], v[198:201], v[40:43]
	v_mfma_f32_16x16x32_bf16 v[48:51], v[158:161], v[198:201], v[48:51]
	v_mfma_f32_16x16x32_bf16 v[60:63], v[150:153], v[206:209], v[60:63]
	v_mfma_f32_16x16x32_bf16 v[64:67], v[158:161], v[206:209], v[64:67]
	v_mfma_f32_16x16x32_bf16 v[0:3], v[154:157], v[186:189], v[0:3]
	v_mfma_f32_16x16x32_bf16 v[4:7], v[162:165], v[186:189], v[4:7]
	v_mfma_f32_16x16x32_bf16 v[20:23], v[154:157], v[194:197], v[20:23]
	v_mfma_f32_16x16x32_bf16 v[24:27], v[162:165], v[194:197], v[24:27]
	v_mfma_f32_16x16x32_bf16 v[40:43], v[154:157], v[202:205], v[40:43]
	v_mfma_f32_16x16x32_bf16 v[48:51], v[162:165], v[202:205], v[48:51]
	v_mfma_f32_16x16x32_bf16 v[60:63], v[154:157], v[210:213], v[60:63]
	v_mfma_f32_16x16x32_bf16 v[64:67], v[162:165], v[210:213], v[64:67]
	s_setprio 0
	s_barrier
	s_add_i32 s2, s5, s17
	v_lshl_add_u64 v[170:171], v[170:171], 0, s[6:7]
	s_mov_b32 m0, s2
	ds_read_b128 v[166:169], v240 offset:49152
	ds_read_b128 v[186:189], v240 offset:50176
	ds_read_b128 v[190:193], v240 offset:51200
	ds_read_b128 v[194:197], v240 offset:52224
	ds_read_b128 v[198:201], v240 offset:53248
	ds_read_b128 v[202:205], v240 offset:54272
	ds_read_b128 v[206:209], v240 offset:55296
	ds_read_b128 v[210:213], v240 offset:56320
	global_load_lds_dwordx4 v[170:171], off
	v_lshl_add_u64 v[170:171], v[214:215], 0, s[6:7]
	s_add_i32 m0, s2, 0x2000
	s_add_i32 s2, s33, s17
	global_load_lds_dwordx4 v[170:171], off
	v_lshl_add_u64 v[170:171], v[216:217], 0, s[6:7]
	s_mov_b32 m0, s2
	s_nop 0
	global_load_lds_dwordx4 v[170:171], off
	v_lshl_add_u64 v[170:171], v[224:225], 0, s[6:7]
	s_add_i32 m0, s2, 0x2000
	s_nop 0
	global_load_lds_dwordx4 v[170:171], off
	v_lshl_add_u64 v[170:171], v[226:227], 0, s[6:7]
	s_mov_b32 m0, s63
	s_nop 0
	global_load_lds_dwordx4 v[170:171], off
	v_lshl_add_u64 v[170:171], v[242:243], 0, s[6:7]
	s_mov_b32 m0, s20
	s_nop 0
	global_load_lds_dwordx4 v[170:171], off
	s_waitcnt vmcnt(8)
	s_waitcnt lgkmcnt(0)
	s_barrier
	s_setprio 1
	v_mfma_f32_16x16x32_bf16 v[68:71], v[134:137], v[166:169], v[68:71]
	v_mfma_f32_16x16x32_bf16 v[72:75], v[142:145], v[166:169], v[72:75]
	v_mfma_f32_16x16x32_bf16 v[92:95], v[134:137], v[190:193], v[92:95]
	v_mfma_f32_16x16x32_bf16 v[96:99], v[142:145], v[190:193], v[96:99]
	v_mfma_f32_16x16x32_bf16 v[108:111], v[134:137], v[198:201], v[108:111]
	v_mfma_f32_16x16x32_bf16 v[112:115], v[142:145], v[198:201], v[112:115]
	v_mfma_f32_16x16x32_bf16 v[124:127], v[134:137], v[206:209], v[124:127]
	v_mfma_f32_16x16x32_bf16 v[128:131], v[142:145], v[206:209], v[128:131]
	v_mfma_f32_16x16x32_bf16 v[68:71], v[138:141], v[186:189], v[68:71]
	v_mfma_f32_16x16x32_bf16 v[72:75], v[146:149], v[186:189], v[72:75]
	v_mfma_f32_16x16x32_bf16 v[92:95], v[138:141], v[194:197], v[92:95]
	v_mfma_f32_16x16x32_bf16 v[96:99], v[146:149], v[194:197], v[96:99]
	v_mfma_f32_16x16x32_bf16 v[108:111], v[138:141], v[202:205], v[108:111]
	v_mfma_f32_16x16x32_bf16 v[112:115], v[146:149], v[202:205], v[112:115]
	v_mfma_f32_16x16x32_bf16 v[124:127], v[138:141], v[210:213], v[124:127]
	v_mfma_f32_16x16x32_bf16 v[128:131], v[146:149], v[210:213], v[128:131]
	v_mfma_f32_16x16x32_bf16 v[52:55], v[150:153], v[166:169], v[52:55]
	v_mfma_f32_16x16x32_bf16 v[56:59], v[158:161], v[166:169], v[56:59]
	v_mfma_f32_16x16x32_bf16 v[76:79], v[150:153], v[190:193], v[76:79]
	v_mfma_f32_16x16x32_bf16 v[84:87], v[158:161], v[190:193], v[84:87]
	v_mfma_f32_16x16x32_bf16 v[100:103], v[150:153], v[198:201], v[100:103]
	v_mfma_f32_16x16x32_bf16 v[104:107], v[158:161], v[198:201], v[104:107]
	v_mfma_f32_16x16x32_bf16 v[116:119], v[150:153], v[206:209], v[116:119]
	v_mfma_f32_16x16x32_bf16 v[120:123], v[158:161], v[206:209], v[120:123]
	v_mfma_f32_16x16x32_bf16 v[52:55], v[154:157], v[186:189], v[52:55]
	v_mfma_f32_16x16x32_bf16 v[56:59], v[162:165], v[186:189], v[56:59]
	v_mfma_f32_16x16x32_bf16 v[76:79], v[154:157], v[194:197], v[76:79]
	v_mfma_f32_16x16x32_bf16 v[84:87], v[162:165], v[194:197], v[84:87]
	v_mfma_f32_16x16x32_bf16 v[100:103], v[154:157], v[202:205], v[100:103]
	v_mfma_f32_16x16x32_bf16 v[104:107], v[162:165], v[202:205], v[104:107]
	v_mfma_f32_16x16x32_bf16 v[116:119], v[154:157], v[210:213], v[116:119]
	v_mfma_f32_16x16x32_bf16 v[120:123], v[162:165], v[210:213], v[120:123]
	s_setprio 0
	s_barrier
	s_add_u32 s0, s0, 0x100
	s_addc_u32 s1, s1, 0
	v_lshl_add_u64 v[132:133], v[132:133], 0, s[8:9]
	v_lshl_add_u64 v[18:19], v[18:19], 0, s[8:9]
	s_cmp_ge_u32 s4, s62
	s_mov_b32 s2, s4
	s_cbranch_scc0 .LBB0_344
	v_readlane_b32 s0, v253, 40
	v_readlane_b32 s1, v253, 41
	s_and_b64 vcc, exec, s[0:1]
	s_cbranch_vccz .LBB0_347
	s_barrier
